# SQ stored fragment-major too (coalesced strip Q loads); remap unconditional in the sq/sk epilogue branch
# speedup vs baseline: 1.0011x; 1.0011x over previous
; #define PG8_LAS __attribute__((address_space(3)))
; __device__ __forceinline__ unsigned cvt_pk_bf16(float lo, float hi) { unsigned r; asm volatile("v_cvt_pk_bf16_f32 %0, %1, %2" : "=v"(r) : "v"(lo), "v"(hi)); return r; }
;     __device__ __forceinline__ void operator()(const f32x4 (&acc)[2][2][4][2], const Unit& u, int wr, int wc, int fr, int fq) const {
;     ...
;         if (grp == 4 || grp == 5) {
;             bf16_t* dst = (bf16_t*)(ws + (grp == 4 ? WS_SQ : WS_SK)); const PG8_LAS float* gn = GL + (grp == 4 ? 0 : 64);
;             const int head = 4 * tq + wc;
;             f32x4 gv[2][2];
; #pragma unroll
;             for (int bj = 0; bj < 2; ++bj)
; #pragma unroll
;                 for (int n = 0; n < 2; ++n) gv[bj][n] = *(const PG8_LAS f32x4*)(gn + 32 * bj + 8 * fq + 4 * n);
; #pragma unroll
;             for (int ai = 0; ai < 2; ++ai)
; #pragma unroll
;                 for (int m = 0; m < 4; ++m) { const int row = row0 + ai * HALF + m * 16; const float rs = rsv[ai][m]; float sq = 0.f; f32x4 t[2][2];
; #pragma unroll
;                     for (int bj = 0; bj < 2; ++bj)
; #pragma unroll
;                         for (int n = 0; n < 2; ++n) { t[bj][n] = acc[ai][bj][m][n] * rs; sq += (t[bj][n][0] * t[bj][n][0] + t[bj][n][1] * t[bj][n][1]) + (t[bj][n][2] * t[bj][n][2] + t[bj][n][3] * t[bj][n][3]); }
;                     sq += __shfl_xor(sq, 16); sq += __shfl_xor(sq, 32);
;                     const float rn = 1.0f / sqrtf(sq * (1.0f / 64.0f) + 1e-6f);
; #pragma unroll
;                     for (int bj = 0; bj < 2; ++bj) { const f32x4 a = t[bj][0] * rn * gv[bj][0], b = t[bj][1] * rn * gv[bj][1];
;                         u32x4 w; w.x = cvt_pk_bf16(a[0], a[1]); w.y = cvt_pk_bf16(a[2], a[3]); w.z = cvt_pk_bf16(b[0], b[1]); w.w = cvt_pk_bf16(b[2], b[3]);
;                         *(u32x4*)(dst + (size_t)row * 512 + head * 64 + 32 * bj + 8 * fq) = w; } }
.LBB0_868:
	v_and_b32_e32 v129, 64, v188
	v_xor_b32_e32 v128, 16, v188
	v_add_u32_e32 v131, 64, v129
	v_cmp_lt_i32_e32 vcc, v128, v131
	s_waitcnt lgkmcnt(0)
	v_pk_mul_f32 v[142:143], v[126:127], v[170:171] op_sel_hi:[1,0]
	v_pk_mul_f32 v[172:173], v[124:125], v[170:171] op_sel_hi:[1,0]
	v_cndmask_b32_e32 v128, v188, v128, vcc
	v_pk_mul_f32 v[124:125], v[142:143], v[142:143]
	v_pk_mul_f32 v[126:127], v[172:173], v[172:173]
	v_pk_mul_f32 v[190:191], v[122:123], v[170:171] op_sel_hi:[1,0]
	v_pk_mul_f32 v[192:193], v[120:121], v[170:171] op_sel_hi:[1,0]
	v_pk_mul_f32 v[138:139], v[116:117], v[170:171] op_sel_hi:[1,0]
	v_lshlrev_b32_e32 v140, 2, v128
	v_pk_mov_b32 v[128:129], v[126:127], v[124:125] op_sel:[1,0]
	v_mov_b32_e32 v127, v125
	v_pk_mul_f32 v[120:121], v[190:191], v[190:191]
	v_pk_mul_f32 v[122:123], v[192:193], v[192:193]
	v_mul_f32_e32 v116, v138, v138
	v_pk_add_f32 v[124:125], v[128:129], v[126:127]
	v_pk_mov_b32 v[126:127], v[122:123], v[120:121] op_sel:[1,0]
	v_mov_b32_e32 v123, v121
	v_pk_mul_f32 v[136:137], v[118:119], v[170:171] op_sel_hi:[1,0]
	v_pk_fma_f32 v[116:117], v[138:139], v[138:139], v[116:117] op_sel_hi:[1,1,0]
	v_pk_add_f32 v[120:121], v[126:127], v[122:123]
	v_mul_f32_e32 v116, v136, v136
	v_pk_add_f32 v[124:125], v[124:125], v[124:125] op_sel_hi:[0,1]
	v_pk_add_f32 v[120:121], v[120:121], v[120:121] op_sel_hi:[0,1]
	v_pk_fma_f32 v[118:119], v[136:137], v[136:137], v[116:117] op_sel_hi:[1,1,0]
	v_pk_mul_f32 v[132:133], v[114:115], v[170:171] op_sel_hi:[1,0]
	v_pk_mul_f32 v[134:135], v[112:113], v[170:171] op_sel_hi:[1,0]
	v_mul_f32_e32 v124, v132, v132
	v_mul_f32_e32 v116, v134, v134
	v_mul_f32_e32 v118, v135, v135
	v_mul_f32_e32 v120, v133, v133
	v_pk_add_f32 v[112:113], v[116:117], v[118:119]
	v_pk_add_f32 v[114:115], v[124:125], v[120:121]
	s_cmp_eq_u32 s1, 4
	v_pk_add_f32 v[112:113], v[112:113], v[114:115]
	v_xor_b32_e32 v114, 32, v188
	v_add_f32_e32 v112, v112, v113
	ds_bpermute_b32 v113, v140, v112
	v_cmp_lt_i32_e32 vcc, v114, v131
	s_cselect_b64 s[4:5], -1, 0
	s_and_b64 s[4:5], s[4:5], exec
	v_cndmask_b32_e32 v114, v188, v114, vcc
	v_lshlrev_b32_e32 v141, 2, v114
	s_waitcnt lgkmcnt(0)
	v_add_f32_e32 v128, v112, v113
	ds_bpermute_b32 v129, v141, v128
	s_cselect_b32 s4, 0, 0x100
	s_mov_b32 s1, 0xae00000
	v_add_u32_e32 v130, s4, v181
	s_cselect_b32 s1, s1, 0xbe40000
	s_mov_b64 s[100:101], -1
	s_waitcnt lgkmcnt(0)
	v_add_f32_e32 v128, v128, v129
	v_fmamk_f32 v128, v128, 0x3c800000, v186
	v_mul_f32_e32 v129, 0x4f800000, v128
	v_cmp_gt_f32_e32 vcc, s50, v128
	ds_read_b128 v[124:127], v130
	ds_read_b128 v[120:123], v130 offset:16
	ds_read_b128 v[116:119], v130 offset:128
	ds_read_b128 v[112:115], v130 offset:144
	v_cndmask_b32_e32 v128, v128, v129, vcc
	v_sqrt_f32_e32 v129, v128
	v_readlane_b32 s4, v237, 2
	v_readlane_b32 s5, v237, 3
	s_add_u32 s8, s4, s1
	v_add_u32_e32 v130, -1, v129
	v_fma_f32 v131, -v130, v129, v128
	s_addc_u32 s9, s5, 0
	s_mov_b32 s98, s8
	s_mov_b32 s99, s9
	v_cmp_ge_f32_e64 s[4:5], 0, v131
	v_add_u32_e32 v131, 1, v129
	s_lshl_b32 s0, s0, 9
	v_cndmask_b32_e64 v130, v129, v130, s[4:5]
	v_fma_f32 v129, -v131, v129, v128
	v_cmp_lt_f32_e64 s[4:5], 0, v129
	s_or_b32 s10, s0, s49
	v_pk_mul_f32 v[94:95], v[94:95], v[168:169] op_sel_hi:[1,0]
	v_cndmask_b32_e64 v129, v130, v131, s[4:5]
	v_mul_f32_e32 v130, 0x37800000, v129
	v_cndmask_b32_e32 v129, v129, v130, vcc
	v_cmp_class_f32_e32 vcc, v128, v187
	v_pk_mul_f32 v[92:93], v[92:93], v[168:169] op_sel_hi:[1,0]
	v_pk_mul_f32 v[84:85], v[84:85], v[168:169] op_sel_hi:[1,0]
	v_cndmask_b32_e32 v128, v129, v128, vcc
	v_div_scale_f32 v129, s[0:1], v128, v128, 1.0
	v_rcp_f32_e32 v170, v129
	s_add_u32 s0, s8, s10
	s_addc_u32 s1, s9, 0
	v_lshl_add_u64 v[130:131], s[0:1], 0, v[152:153]
	v_fma_f32 v189, -v129, v170, 1.0
	v_fmac_f32_e32 v170, v189, v170
	v_div_scale_f32 v189, vcc, 1.0, v128, 1.0
	v_mul_f32_e32 v194, v189, v170
	v_fma_f32 v195, -v129, v194, v189
	v_fmac_f32_e32 v194, v195, v170
	v_fma_f32 v129, -v129, v194, v189
	v_div_fmas_f32 v129, v129, v170, v194
	v_div_fixup_f32 v170, v129, v128, 1.0
	v_pk_mul_f32 v[142:143], v[142:143], v[170:171] op_sel_hi:[1,0]
	v_pk_mul_f32 v[172:173], v[172:173], v[170:171] op_sel_hi:[1,0]
	s_waitcnt lgkmcnt(0)
	v_pk_mul_f32 v[142:143], v[126:127], v[142:143]
	v_pk_mul_f32 v[190:191], v[190:191], v[170:171] op_sel_hi:[1,0]
	v_lshlrev_b64 v[128:129], 10, v[166:167]
	v_pk_mul_f32 v[172:173], v[124:125], v[172:173]
	v_pk_mul_f32 v[192:193], v[192:193], v[170:171] op_sel_hi:[1,0]
	v_pk_mul_f32 v[194:195], v[122:123], v[190:191]
	v_cvt_pk_bf16_f32 v190, v172, v173
	v_cvt_pk_bf16_f32 v191, v142, v143
	v_mov_b32_e32 v142, v171
	v_lshl_add_u64 v[128:129], v[130:131], 0, v[128:129]
	v_pk_mul_f32 v[192:193], v[120:121], v[192:193]
	v_pk_mul_f32 v[110:111], v[110:111], v[142:143] op_sel_hi:[1,0]
	v_pk_mul_f32 v[108:109], v[108:109], v[142:143] op_sel_hi:[1,0]
	v_cvt_pk_bf16_f32 v192, v192, v193
	v_cvt_pk_bf16_f32 v193, v194, v195
	s_mov_b64 vcc, s[100:101]
	s_cbranch_vccz .Lrm_orig_16
	v_accvgpr_write_b32 a0, v224
	v_accvgpr_write_b32 a1, v225
	v_accvgpr_write_b32 a2, v226
	v_accvgpr_write_b32 a3, v228
	v_accvgpr_write_b32 a4, v229
	v_subrev_u32_e32 v224, s98, v128
	v_lshrrev_b32_e32 v225, 10, v224
	v_and_b32_e32 v226, 0x3ff, v224
	v_lshrrev_b32_e32 v228, 7, v226
	v_mul_u32_u24_e32 v228, 0x204000, v228
	v_and_b32_e32 v226, 0x70, v226
	v_lshl_add_u32 v228, v226, 5, v228
	v_add_u32_e32 v229, 0x80, v225
	v_and_b32_e32 v226, 0xff, v225
	v_cmp_gt_u32_e32 vcc, 16, v226
	v_and_b32_e32 v224, 63, v226
	v_add_u32_e32 v226, 0x70, v226
	s_nop 1
	v_cndmask_b32_e32 v224, v224, v226, vcc
	v_cmp_lt_u32_e32 vcc, 0x3fff, v225
	s_nop 2
	v_cndmask_b32_e32 v229, v229, v224, vcc
	v_lshrrev_b32_e32 v224, 5, v229
	v_lshl_add_u32 v228, v224, 12, v228
	v_and_b32_e32 v224, 31, v229
	v_lshl_add_u32 v228, v224, 4, v228
	v_mov_b32_e32 v229, 0
	v_lshl_add_u64 v[224:225], s[98:99], 0, v[228:229]
	v_cmp_ne_u32_e64 vcc, s100, 0
	s_nop 2
	v_cndmask_b32_e32 v224, v128, v224, vcc
	v_cndmask_b32_e32 v225, v129, v225, vcc
	global_store_dwordx4 v[224:225], v[190:193], off
	s_nop 1
	v_accvgpr_read_b32 v224, a0
	v_accvgpr_read_b32 v225, a1
	v_accvgpr_read_b32 v226, a2
	v_accvgpr_read_b32 v228, a3
	v_accvgpr_read_b32 v229, a4
	s_branch .Lrm_done_16

; #define LAS __attribute__((address_space(3)))
; __device__ __forceinline__ void sb_load(SbTile& t, const bf16* SK, const bf16* SV, int h, int kt, int lane) {
;     const bf16* kp = SK + (size_t)pos2row(kt + (lane & 31)) * 512 + h * 64 + 8 * (lane >> 5);
;     const bf16* vp = SV + (size_t)pos2row(kt + (lane >> 1)) * 512 + h * 64 + 32 * (lane & 1);
; #pragma unroll
;     for (int j = 0; j < 4; ++j) { t.k[j] = *(const bf16x8*)(kp + 16 * j); t.v[j] = *(const u32x4*)(vp + 8 * j); }
; }
; __device__ __forceinline__ void sb_strip(const bf16* SQ, const bf16* SK, const bf16* SV, bf16* OMIX, int h, int qpos0, int lane, LAS unsigned char* vl) {
;     const int l32 = lane & 31, hi = lane >> 5;
;     const int qrow = qpos0 - 128 + l32;
;     SbTile t0, t1, t2;
;     sb_load(t0, SK, SV, h, qpos0, lane); sb_load(t1, SK, SV, h, qpos0 - 32, lane);
;     bf16x8 qf[4];
;     { const bf16* qp = SQ + (size_t)qrow * 512 + h * 64 + 8 * hi;
; #pragma unroll
;       for (int j = 0; j < 4; ++j) qf[j] = *(const bf16x8*)(qp + 16 * j); }
;     f32x16 o0, o1;
; #pragma unroll
;     for (int r = 0; r < 16; ++r) { o0[r] = 0.f; o1[r] = 0.f; }
;     float carry = 0.f;
;     const int qpos = qpos0 + l32;
;     LAS unsigned char* vw = vl + (lane >> 1) * 144 + (lane & 1) * 64;
;     const LAS unsigned char* vr = vl + (4 * hi + ((lane & 15) >> 2)) * 144 + (16 * ((lane >> 4) & 1) + 4 * (lane & 3)) * 2;
.LBB0_1043:
	s_lshl_b32 s4, s28, 5
	s_and_b32 s6, s4, 0x3fe0
	s_add_i32 s4, s6, 0x80
	v_or_b32_e32 v202, s4, v181
	v_add_u32_e32 v0, 0xffffff80, v202
	s_ashr_i32 s4, s28, 3
	v_lshlrev_b64 v[2:3], 10, v[0:1]
	s_and_b32 s24, s4, 0xffffffc0
	v_or_b32_e32 v0, s6, v193
	s_ashr_i32 s25, s24, 31
	v_lshlrev_b32_e32 v0, 10, v0
	v_lshl_add_u64 v[2:3], s[20:21], 0, v[2:3]
	s_lshl_b64 s[4:5], s[24:25], 1
	v_lshl_add_u64 v[4:5], s[22:23], 0, v[0:1]
	v_or_b32_e32 v192, s6, v181
	v_lshl_add_u64 v[2:3], v[2:3], 0, s[4:5]
	v_lshl_add_u64 v[4:5], v[4:5], 0, s[4:5]
	s_addk_i32 s6, 0x60
	s_mul_i32 s100, s24, 0x8100
	v_lshlrev_b32_e32 v222, 4, v201
	v_add_u32_e32 v222, s100, v222
	v_mov_b32_e32 v223, 0
	v_lshl_add_u64 v[218:219], s[20:21], 0, v[222:223]
	v_lshl_add_u64 v[230:231], s[22:23], 0, v[222:223]
	v_mov_b32_e32 v222, s6
	v_lshlrev_b32_e32 v222, 7, v222
	v_lshl_add_u64 v[226:227], v[218:219], 0, v[222:223]
	v_lshl_add_u64 v[234:235], v[230:231], 0, v[222:223]
	v_add_u32_e32 v222, 0x1000, v222
	v_lshl_add_u64 v[224:225], v[218:219], 0, v[222:223]
	v_lshl_add_u64 v[232:233], v[230:231], 0, v[222:223]
	s_and_b32 s46, s30, 0x3fe0
	v_lshl_add_u64 v[2:3], v[2:3], 0, v[186:187]
	v_lshl_add_u64 v[4:5], v[4:5], 0, v[188:189]
	v_or_b32_e32 v0, s6, v181
	global_load_dwordx4 v[118:121], v[232:233], off offset:3072
	global_load_dwordx4 v[126:129], v[232:233], off offset:2048
	global_load_dwordx4 v[130:133], v[232:233], off offset:1024
	global_load_dwordx4 v[134:137], v[232:233], off
	global_load_dwordx4 v[90:93], v[224:225], off
	global_load_dwordx4 v[94:97], v[224:225], off offset:1024
	global_load_dwordx4 v[86:89], v[224:225], off offset:2048
	global_load_dwordx4 v[82:85], v[224:225], off offset:3072
	s_cmpk_gt_u32 s6, 0x7f
	v_add_u32_e32 v2, 0xffffff80, v0
	v_max_u32_e32 v0, 0x70, v0
	v_add_u32_e32 v0, 0x3f90, v0
	s_cselect_b64 vcc, -1, 0
	v_cndmask_b32_e32 v0, v0, v2, vcc
	v_lshlrev_b64 v[2:3], 10, v[0:1]
	v_or_b32_e32 v0, s6, v193
	v_add_u32_e32 v4, 0xffffff80, v0
	v_max_u32_e32 v0, 0x70, v0
	v_add_u32_e32 v0, 0x3f90, v0
	v_cndmask_b32_e32 v0, v0, v4, vcc
	v_lshlrev_b64 v[4:5], 10, v[0:1]
	v_lshl_add_u64 v[4:5], s[22:23], 0, v[4:5]
	v_lshl_add_u64 v[2:3], s[20:21], 0, v[2:3]
	v_lshl_add_u64 v[4:5], v[4:5], 0, s[4:5]
	v_lshl_add_u64 v[2:3], v[2:3], 0, s[4:5]
	v_lshl_add_u64 v[4:5], v[4:5], 0, v[188:189]
	v_readlane_b32 s6, v237, 35
	v_lshl_add_u64 v[2:3], v[2:3], 0, v[186:187]
	global_load_dwordx4 v[146:149], v[234:235], off offset:3072
	global_load_dwordx4 v[150:153], v[234:235], off offset:2048
	global_load_dwordx4 v[154:157], v[234:235], off offset:1024
	global_load_dwordx4 v[158:161], v[234:235], off
	global_load_dwordx4 v[102:105], v[226:227], off
	global_load_dwordx4 v[110:113], v[226:227], off offset:1024
	global_load_dwordx4 v[106:109], v[226:227], off offset:2048
	global_load_dwordx4 v[98:101], v[226:227], off offset:3072
	v_lshlrev_b32_e32 v0, 10, v192
	v_readlane_b32 s7, v237, 36
	v_mov_b32_e32 v14, v1
	v_mov_b32_e32 v15, v1
	v_lshl_add_u64 v[2:3], s[6:7], 0, v[0:1]
	v_lshl_add_u64 v[2:3], v[2:3], 0, s[4:5]
	v_lshl_add_u64 v[2:3], v[2:3], 0, v[190:191]
	s_mov_b32 s100, 0xfefc0000
	s_mov_b32 s101, -1
	v_lshl_add_u64 v[222:223], v[224:225], 0, s[100:101]
	global_load_dwordx4 v[66:69], v[222:223], off
	global_load_dwordx4 v[70:73], v[222:223], off offset:1024
	global_load_dwordx4 v[74:77], v[222:223], off offset:2048
	global_load_dwordx4 v[78:81], v[222:223], off offset:3072
	v_mov_b32_e32 v0, v1
	v_mov_b32_e32 v2, v1
	v_mov_b32_e32 v3, v1
	v_mov_b32_e32 v4, v1
	v_mov_b32_e32 v5, v1
	v_mov_b32_e32 v6, v1
	v_mov_b32_e32 v7, v1
	v_mov_b32_e32 v8, v1
	v_mov_b32_e32 v9, v1
	v_mov_b32_e32 v10, v1
	v_mov_b32_e32 v11, v1
	v_mov_b32_e32 v12, v1
	v_mov_b32_e32 v13, v1
	v_mov_b64_e32 v[32:33], v[14:15]
	v_mov_b64_e32 v[30:31], v[12:13]
	v_mov_b64_e32 v[28:29], v[10:11]
	v_mov_b64_e32 v[26:27], v[8:9]
	v_mov_b64_e32 v[24:25], v[6:7]
	v_mov_b64_e32 v[22:23], v[4:5]
	v_mov_b64_e32 v[20:21], v[2:3]
	v_mov_b64_e32 v[18:19], v[0:1]
	v_mov_b64_e32 v[16:17], v[14:15]
	v_or_b32_e32 v203, s46, v193
	v_or_b32_e32 v204, s46, v181
	v_or_b32_e32 v205, s46, v180
	v_lshl_add_u64 v[194:195], v[182:183], 0, s[4:5]
	v_lshl_add_u64 v[196:197], v[184:185], 0, s[4:5]
	s_mov_b32 s47, 0
	v_mov_b32_e32 v208, v1
	v_mov_b64_e32 v[14:15], v[12:13]
	v_mov_b64_e32 v[12:13], v[10:11]
	v_mov_b64_e32 v[10:11], v[8:9]
	v_mov_b64_e32 v[8:9], v[6:7]
	v_mov_b64_e32 v[6:7], v[4:5]
	v_mov_b64_e32 v[4:5], v[2:3]
	v_mov_b64_e32 v[2:3], v[0:1]
	s_branch .LBB0_1046
